# tile-granular late prep (stride gridDim-64) + rw_chunk_prep head loads issued in one burst
# speedup vs baseline: 1.0110x; 1.0048x over previous
; __global__ void __launch_bounds__(NTHR, 2) hybrid_fwd(Args args) {
;     ...
;         for (int tile = blockIdx.x; tile < T / 32; tile += F.G) p2_rwprep_tile(F, args, tile * 32); }
.Lrw_step:
	s_movk_i32 s100, 0xff
	s_add_i32 s101, s97, -64
	s_cmp_eq_u32 s98, 1
	s_cselect_b32 s101, s101, s97
	s_cselect_b32 s100, 0x1ff, s100
	s_add_i32 s56, s56, s101
	s_cmp_gt_i32 s56, s100
	s_cbranch_scc1 .LBB0_347

; #define LAS __attribute__((address_space(3)))
; __device__ __forceinline__ f32x4 bf4(v2u u) { return (f32x4){bflo(u.x), bfhi(u.x), bflo(u.y), bfhi(u.y)}; }
; #define MFMA32(a, b, c) __builtin_amdgcn_mfma_f32_16x16x32_bf16(a, b, c, 0, 0, 0)
; __device__ __forceinline__ void rw_chunk_prep(const Args& a, int head, int tc0, const LAS bf16* TDr, const LAS bf16* DAr, LAS unsigned char* lw_, int lane) {
;     ...
;     {   bf16x8 atd[2], ada[2];
; #pragma unroll
;         for (int kk = 0; kk < 2; ++kk) { atd[kk] = *(const LAS bf16x8*)(TDr + j * 64 + kk * 32 + kg * 8); ada[kk] = *(const LAS bf16x8*)(DAr + j * 64 + kk * 32 + kg * 8); }
; #pragma unroll
;         for (int cb = 0; cb < 4; ++cb) { accw[cb] = (f32x4){0.f, 0.f, 0.f, 0.f}; acca[cb] = (f32x4){0.f, 0.f, 0.f, 0.f};
; #pragma unroll
;             for (int kk = 0; kk < 2; ++kk) { const bf16x8 bw = *(const bf16x8*)(W2t + (size_t)(cbase + cb) * 64 + kk * 32 + kg * 8), ba = *(const bf16x8*)(A2t + (size_t)(cbase + cb) * 64 + kk * 32 + kg * 8);
;                 accw[cb] = MFMA32(atd[kk], bw, accw[cb]); acca[cb] = MFMA32(ada[kk], ba, acca[cb]); } }
;     }
;     const f32x4 w0 = ld4(a.in[9] + cbase), a0 = ld4(a.in[11] + cbase), kkw = ld4(a.in[13] + cbase), kaw = ld4(a.in[14] + cbase), rkw = ld4(a.in[15] + cbase);
;     const f32x4 mur = ld4(a.in[4] + cbase), muk = ld4(a.in[5] + cbase), muv = ld4(a.in[6] + cbase);
;     float* RK = (float*)(ws + WS_RK);
;     f32x4 rr[4], km[4], av[4], bv[4], lw[4], vv[4];
;     {   const int tt0 = tc0 + 4 * rg; const f32x4 zero = {0.f, 0.f, 0.f, 0.f};
;         f32x4 pr = tt0 > 0 ? bf4(*(const v2u*)(ZA + (size_t)(tt0 - 1) * 3072 + cbase)) : zero;
;         f32x4 pk = tt0 > 0 ? bf4(*(const v2u*)(ZA + (size_t)(tt0 - 1) * 3072 + 1024 + cbase)) : zero;
;         f32x4 pv = tt0 > 0 ? bf4(*(const v2u*)(ZA + (size_t)(tt0 - 1) * 3072 + 2048 + cbase)) : zero;
.LBB0_329:
	s_lshr_b32 s0, s59, 1
	s_add_i32 s0, s0, s34
	s_and_b32 s2, s58, 16
	v_lshl_add_u32 v208, s2, 7, v155
	v_lshl_or_b32 v66, s0, 6, v154
	ds_read_b128 v[246:249], v208
	ds_read_b128 v[250:253], v208 offset:4096
	ds_read_b128 v[204:207], v208 offset:64
	ds_read_b128 v[132:135], v208 offset:4160
	v_lshlrev_b64 v[140:141], 7, v[66:67]
	v_lshl_add_u64 v[142:143], v[74:75], 0, v[140:141]
	v_lshl_add_u64 v[144:145], v[76:77], 0, v[140:141]
	global_load_dwordx4 v[4:7], v[142:143], off
	global_load_dwordx4 v[24:27], v[144:145], off
	global_load_dwordx4 v[214:217], v[142:143], off offset:64
	global_load_dwordx4 v[230:233], v[144:145], off offset:64
	global_load_dwordx4 v[8:11], v[142:143], off offset:128
	global_load_dwordx4 v[28:31], v[144:145], off offset:128
	global_load_dwordx4 v[218:221], v[142:143], off offset:192
	global_load_dwordx4 v[234:237], v[144:145], off offset:192
	global_load_dwordx4 v[12:15], v[142:143], off offset:256
	global_load_dwordx4 v[32:35], v[144:145], off offset:256
	global_load_dwordx4 v[222:225], v[142:143], off offset:320
	global_load_dwordx4 v[238:241], v[144:145], off offset:320
	global_load_dwordx4 v[16:19], v[142:143], off offset:384
	global_load_dwordx4 v[56:59], v[144:145], off offset:384
	global_load_dwordx4 v[226:229], v[142:143], off offset:448
	global_load_dwordx4 v[242:245], v[144:145], off offset:448
	v_lshlrev_b64 v[140:141], 2, v[66:67]
	v_lshl_add_u64 v[146:147], s[38:39], 0, v[140:141]
	global_load_dwordx4 v[20:23], v[146:147], off
	v_lshl_add_u64 v[146:147], s[42:43], 0, v[140:141]
	global_load_dwordx4 v[60:63], v[146:147], off
	v_lshl_add_u64 v[146:147], s[46:47], 0, v[140:141]
	global_load_dwordx4 v[36:39], v[146:147], off
	v_lshl_add_u64 v[146:147], s[48:49], 0, v[140:141]
	global_load_dwordx4 v[52:55], v[146:147], off
	v_lshl_add_u64 v[146:147], s[50:51], 0, v[140:141]
	global_load_dwordx4 v[40:43], v[146:147], off
	v_lshl_add_u64 v[146:147], s[76:77], 0, v[140:141]
	global_load_dwordx4 v[44:47], v[146:147], off
	v_lshl_add_u64 v[146:147], s[78:79], 0, v[140:141]
	global_load_dwordx4 v[48:51], v[146:147], off
	v_lshl_add_u64 v[146:147], s[80:81], 0, v[140:141]
	global_load_dwordx4 v[0:3], v[146:147], off
	v_lshlrev_b32_e32 v66, 1, v66
	s_or_b32 s60, s2, s57
	v_add_u32_e32 v106, s60, v157
	v_add_u32_e32 v96, -1, v106
	v_mov_b64_e32 v[148:149], s[72:73]
	v_mad_u64_u32 v[148:149], s[26:27], v96, s44, v[148:149]
	v_lshl_add_u64 v[148:149], v[148:149], 0, v[66:67]
	v_add_co_u32_e32 v148, vcc, 0x800, v148
	s_nop 1
	v_addc_co_u32_e32 v149, vcc, 0, v149, vcc
	v_cmp_lt_i32_e32 vcc, 0, v106
	v_mov_b32_e32 v100, 0
	v_mov_b32_e32 v101, 0
	v_mov_b32_e32 v104, 0
	v_mov_b32_e32 v105, 0
	v_mov_b32_e32 v150, 0
	v_mov_b32_e32 v151, 0
	s_and_saveexec_b64 s[2:3], vcc
	global_load_dwordx2 v[100:101], v[148:149], off offset:-2048
	global_load_dwordx2 v[104:105], v[148:149], off
	global_load_dwordx2 v[150:151], v[148:149], off offset:2048
	s_or_b64 exec, exec, s[2:3]
	s_waitcnt vmcnt(11) lgkmcnt(0)
	v_mfma_f32_16x16x32_bf16 v[4:7], v[246:249], v[4:7], 0
	v_mfma_f32_16x16x32_bf16 v[24:27], v[250:253], v[24:27], 0
	v_mfma_f32_16x16x32_bf16 v[8:11], v[246:249], v[8:11], 0
	v_mfma_f32_16x16x32_bf16 v[28:31], v[250:253], v[28:31], 0
	v_mfma_f32_16x16x32_bf16 v[12:15], v[246:249], v[12:15], 0
	v_mfma_f32_16x16x32_bf16 v[32:35], v[250:253], v[32:35], 0
	v_mfma_f32_16x16x32_bf16 v[16:19], v[246:249], v[16:19], 0
	v_mfma_f32_16x16x32_bf16 v[56:59], v[250:253], v[56:59], 0
	v_mfma_f32_16x16x32_bf16 v[4:7], v[204:207], v[214:217], v[4:7]
	v_mfma_f32_16x16x32_bf16 v[24:27], v[132:135], v[230:233], v[24:27]
	v_mfma_f32_16x16x32_bf16 v[8:11], v[204:207], v[218:221], v[8:11]
	v_mfma_f32_16x16x32_bf16 v[28:31], v[132:135], v[234:237], v[28:31]
	v_mfma_f32_16x16x32_bf16 v[12:15], v[204:207], v[222:225], v[12:15]
	v_mfma_f32_16x16x32_bf16 v[32:35], v[132:135], v[238:241], v[32:35]
	v_mfma_f32_16x16x32_bf16 v[16:19], v[204:207], v[226:229], v[16:19]
	v_mfma_f32_16x16x32_bf16 v[56:59], v[132:135], v[242:245], v[56:59]
	s_waitcnt vmcnt(0)
; __device__ __forceinline__ f32x4 bf4(v2u u) { return (f32x4){bflo(u.x), bfhi(u.x), bflo(u.y), bfhi(u.y)}; }
; __device__ __forceinline__ void rw_chunk_prep(const Args& a, int head, int tc0, const LAS bf16* TDr, const LAS bf16* DAr, LAS unsigned char* lw_, int lane) {
;     ...
;         f32x4 pr = tt0 > 0 ? bf4(*(const v2u*)(ZA + (size_t)(tt0 - 1) * 3072 + cbase)) : zero;
;         f32x4 pk = tt0 > 0 ? bf4(*(const v2u*)(ZA + (size_t)(tt0 - 1) * 3072 + 1024 + cbase)) : zero;
;         f32x4 pv = tt0 > 0 ? bf4(*(const v2u*)(ZA + (size_t)(tt0 - 1) * 3072 + 2048 + cbase)) : zero;
; #pragma unroll
;         for (int i = 0; i < 4; ++i) {
;             const int tt = tt0 + i;
;             const f32x4 zr = bf4(*(const v2u*)(ZA + (size_t)tt * 3072 + cbase)), zk = bf4(*(const v2u*)(ZA + (size_t)tt * 3072 + 1024 + cbase)), zv = bf4(*(const v2u*)(ZA + (size_t)tt * 3072 + 2048 + cbase));
;             const f32x4 r = zr + (pr - zr) * mur, k = zk + (pk - zk) * muk, v = zv + (pv - zv) * muv;
;             pr = zr; pk = zk; pv = zv;
;             f32x4 lwv, alr;
; #pragma unroll
;             for (int cb = 0; cb < 4; ++cb) { const float x = -(w0[cb] + accw[cb][i]); const float sp = fmaxf(x, 0.f) + __logf(1.f + __expf(-fabsf(x))); lwv[cb] = -__expf(-sp - 0.5f); alr[cb] = __builtin_amdgcn_rcpf(1.f + __expf(-(a0[cb] + acca[cb][i]))); }
;             const f32x4 kkr = k * kkw, kmod = k * (1.f + (alr - 1.f) * kaw);
;             float ssq = (kkr.x * kkr.x + kkr.y * kkr.y) + (kkr.z * kkr.z + kkr.w * kkr.w);
;             const f32x4 rkk = r * kmod * rkw; float rkp = (rkk.x + rkk.y) + (rkk.z + rkk.w);
;             ssq = row16_sum(ssq); rkp = row16_sum(rkp);
;             const float inv = __builtin_amdgcn_rsqf(fmaxf(ssq, 1e-24f));
;             const f32x4 kk = kkr * inv;
;             rr[i] = r; km[i] = kmod; av[i] = -kk; bv[i] = kk * alr; lw[i] = lwv; vv[i] = v;
;             if (j == 0) RK[(size_t)tt * 16 + head] = rkp;
	v_lshlrev_b32_e32 v98, 16, v100
	v_and_b32_e32 v100, 0xffff0000, v100
	v_lshlrev_b32_e32 v99, 16, v101
	v_and_b32_e32 v101, 0xffff0000, v101
	v_lshlrev_b32_e32 v102, 16, v104
	v_and_b32_e32 v103, 0xffff0000, v104
	v_lshlrev_b32_e32 v104, 16, v105
	v_and_b32_e32 v105, 0xffff0000, v105
	v_lshlrev_b32_e32 v186, 16, v150
	v_and_b32_e32 v188, 0xffff0000, v150
	v_lshlrev_b32_e32 v187, 16, v151
	v_and_b32_e32 v189, 0xffff0000, v151
	v_mov_b64_e32 v[96:97], s[72:73]
	v_mad_i64_i32 v[96:97], s[2:3], v106, s44, v[96:97]
	v_lshl_add_u64 v[96:97], v[96:97], 0, v[66:67]
	global_load_dwordx2 v[108:109], v[96:97], off
	global_load_dwordx2 v[110:111], v[96:97], off offset:2048
	v_add_co_u32_e32 v96, vcc, s45, v96
	s_waitcnt vmcnt(8)
	v_add_f32_e32 v107, v24, v60
	v_addc_co_u32_e32 v97, vcc, 0, v97, vcc
	global_load_dwordx2 v[96:97], v[96:97], off
	v_add_f32_e32 v28, v28, v61
	v_add_f32_e32 v32, v32, v62
	v_add_f32_e32 v56, v56, v63
	v_mul_f32_e32 v107, 0xbfb8aa3b, v107
	v_mul_f32_e32 v28, 0xbfb8aa3b, v28
	v_mul_f32_e32 v32, 0xbfb8aa3b, v32
	v_mul_f32_e32 v56, 0xbfb8aa3b, v56
	v_exp_f32_e32 v107, v107
	v_exp_f32_e32 v28, v28
	v_exp_f32_e32 v32, v32
	v_exp_f32_e32 v56, v56
	v_add_f32_e32 v107, 1.0, v107
	v_add_f32_e32 v28, 1.0, v28
	v_add_f32_e32 v32, 1.0, v32
	v_add_f32_e32 v56, 1.0, v56
	v_rcp_f32_e32 v112, v107
	v_rcp_f32_e32 v114, v32
	v_rcp_f32_e32 v115, v56
	v_rcp_f32_e32 v113, v28
	s_lshl_b64 s[2:3], s[0:1], 2
	v_mov_b32_e32 v190, v67
	v_pk_add_f32 v[116:117], v[114:115], -1.0 op_sel_hi:[1,0]
	v_pk_add_f32 v[118:119], v[112:113], -1.0 op_sel_hi:[1,0]
	s_waitcnt vmcnt(7)
	v_pk_fma_f32 v[130:131], v[54:55], v[116:117], 1.0 op_sel_hi:[1,1,0]
	v_pk_fma_f32 v[128:129], v[52:53], v[118:119], 1.0 op_sel_hi:[1,1,0]
	v_mov_b32_e32 v24, v67
	s_add_u32 s26, s35, s2
	s_addc_u32 s27, s36, s3
	s_waitcnt vmcnt(2)
	v_lshlrev_b32_e32 v122, 16, v108
	v_and_b32_e32 v123, 0xffff0000, v108
	v_lshlrev_b32_e32 v124, 16, v109
	s_waitcnt vmcnt(1)
	v_lshlrev_b32_e32 v120, 16, v110
	v_and_b32_e32 v121, 0xffff0000, v110
	v_lshlrev_b32_e32 v126, 16, v111
	v_and_b32_e32 v127, 0xffff0000, v111
	v_and_b32_e32 v125, 0xffff0000, v109
	v_sub_f32_e32 v109, v100, v123
	v_sub_f32_e32 v108, v98, v122
	v_sub_f32_e32 v100, v99, v124
	v_sub_f32_e32 v99, v105, v127
	v_sub_f32_e32 v98, v104, v126
	v_sub_f32_e32 v103, v103, v121
	v_sub_f32_e32 v102, v102, v120
	v_sub_f32_e32 v101, v101, v125
	v_pk_fma_f32 v[102:103], v[48:49], v[102:103], v[120:121]
	v_pk_fma_f32 v[98:99], v[50:51], v[98:99], v[126:127]
	v_pk_fma_f32 v[110:111], v[46:47], v[100:101], v[124:125]
	v_pk_fma_f32 v[108:109], v[44:45], v[108:109], v[122:123]
	v_pk_mul_f32 v[118:119], v[38:39], v[98:99]
	v_pk_mul_f32 v[116:117], v[36:37], v[102:103]
	v_pk_mul_f32 v[100:101], v[130:131], v[98:99]
	v_pk_mul_f32 v[102:103], v[128:129], v[102:103]
	v_pk_mul_f32 v[98:99], v[118:119], v[118:119]
	v_pk_mul_f32 v[104:105], v[116:117], v[116:117]
	v_pk_mul_f32 v[128:129], v[108:109], v[102:103]
	v_pk_mul_f32 v[130:131], v[110:111], v[100:101]
	v_pk_mov_b32 v[132:133], v[104:105], v[98:99] op_sel:[1,0]
	v_mov_b32_e32 v105, v99
	v_pk_mul_f32 v[98:99], v[42:43], v[130:131]
	v_pk_mul_f32 v[128:129], v[40:41], v[128:129]
	v_pk_add_f32 v[104:105], v[132:133], v[104:105]
	v_add_f32_e32 v28, v128, v129
	v_add_f32_e32 v32, v98, v99
	v_add_f32_e32 v56, v104, v105
	v_add_f32_e32 v28, v28, v32
	s_nop 0
	v_add_f32_dpp v32, v56, v56 quad_perm:[1,0,3,2] row_mask:0xf bank_mask:0xf bound_ctrl:1
	v_add_f32_dpp v28, v28, v28 quad_perm:[1,0,3,2] row_mask:0xf bank_mask:0xf bound_ctrl:1
	s_nop 0
	v_add_f32_dpp v32, v32, v32 quad_perm:[2,3,0,1] row_mask:0xf bank_mask:0xf bound_ctrl:1
	v_add_f32_dpp v28, v28, v28 quad_perm:[2,3,0,1] row_mask:0xf bank_mask:0xf bound_ctrl:1
	s_nop 0
	v_add_f32_dpp v191, v32, v32 row_half_mirror row_mask:0xf bank_mask:0xf bound_ctrl:1
	v_add_f32_dpp v28, v28, v28 row_half_mirror row_mask:0xf bank_mask:0xf bound_ctrl:1
	s_nop 0
	v_mov_b32_dpp v190, v191 row_mirror row_mask:0xf bank_mask:0xf
	v_mov_b32_dpp v24, v28 row_mirror row_mask:0xf bank_mask:0xf
	s_and_saveexec_b64 s[2:3], s[24:25]
	s_cbranch_execz .LBB0_337
	v_ashrrev_i32_e32 v107, 31, v106
	v_lshlrev_b64 v[98:99], 6, v[106:107]
	v_lshl_add_u64 v[98:99], s[26:27], 0, v[98:99]
	v_add_f32_e32 v24, v28, v24
	global_store_dword v[98:99], v24, off
